# v49 + grid-barrier entry: workspace-pointer kernarg load issued before the store drain and workgroup barrier (9 sites)
# baseline (speedup 1.0000x reference)
; #define LAS __attribute__((address_space(3)))
; __device__ __forceinline__ unsigned xb_add(unsigned* p, unsigned v) { return __hip_atomic_fetch_add(p, v, __ATOMIC_RELAXED, __HIP_MEMORY_SCOPE_AGENT); }
; __device__ __forceinline__ unsigned xb_xcc_id() { return (unsigned)__builtin_amdgcn_s_getreg((3 << 11) | 20) & 0xFu; }
; __device__ __forceinline__ void xcd_barrier(unsigned* bar, volatile LAS unsigned* st) {
;     asm volatile("s_waitcnt vmcnt(0)" ::: "memory");
;     __syncthreads();
;     if (threadIdx.x == 0) {
;         const unsigned x = xb_xcc_id();
;         __builtin_amdgcn_s_waitcnt(0);
;         unsigned nloc = st[0], nx = st[1];
;         if (nloc == 0u) { xcd_barrier_complete(bar, x, nloc, nx); st[0] = nloc; st[1] = nx; }
;         const unsigned old = xb_add(&bar[XB_XSUB(x)], 1u);
.LBB0_75:
	s_cmp_lt_i32 s89, 2
	s_waitcnt lgkmcnt(0)
	s_barrier
	s_cbranch_scc1 .LBB0_129
	v_readlane_b32 s4, v254, 0
	v_readlane_b32 s5, v254, 1
	s_load_dwordx2 s[4:5], s[4:5], 0xb8
	s_waitcnt vmcnt(0)
	s_barrier
	s_mov_b64 s[0:1], exec
	v_readlane_b32 s6, v254, 4
	v_readlane_b32 s7, v254, 5
	s_and_b64 s[6:7], s[0:1], s[6:7]
	s_mov_b64 exec, s[6:7]
	s_cbranch_execz .LBB0_128
	s_add_i32 s7, 0, 0x20800
	v_mov_b32_e32 v0, s7
	s_getreg_b32 s6, hwreg(HW_REG_XCC_ID, 0, 4)
	s_waitcnt vmcnt(0) expcnt(0) lgkmcnt(0)
	ds_read_b32 v2, v0
	s_add_i32 s7, 0, 0x20804
	v_mov_b32_e32 v0, s7
	ds_read_b32 v0, v0
	s_and_b32 s33, s6, 15
	s_waitcnt lgkmcnt(1)
	v_cmp_ne_u32_e32 vcc, 0, v2
	s_cbranch_vccnz .LBB0_92
	v_readlane_b32 s6, v254, 2
	v_readlane_b32 s7, v254, 3
	s_load_dwordx2 s[10:11], s[6:7], 0x4
	s_add_u32 s6, s4, 0x39400200
	s_addc_u32 s7, s5, 0
	s_add_u32 s8, s4, 0x39400400
	s_addc_u32 s9, s5, 0
	s_waitcnt lgkmcnt(0)
	s_mul_i32 s42, s10, s3
	s_add_u32 s10, s4, 0x39400500
	s_mul_i32 s42, s42, s11
	s_addc_u32 s11, s5, 0
	s_add_u32 s12, s4, 0x39400600
	s_addc_u32 s13, s5, 0
	s_add_u32 s14, s4, 0x39400700
	s_addc_u32 s15, s5, 0
	s_add_u32 s16, s4, 0x39400800
	s_addc_u32 s17, s5, 0
	s_add_u32 s18, s4, 0x39400900
	s_addc_u32 s19, s5, 0
	s_add_u32 s20, s4, 0x39400a00
	s_addc_u32 s21, s5, 0
	s_add_u32 s22, s4, 0x39400b00
	s_addc_u32 s23, s5, 0
	s_add_u32 s24, s4, 0x39400c00
	s_addc_u32 s25, s5, 0
	s_add_u32 s26, s4, 0x39400d00
	s_addc_u32 s27, s5, 0
	s_add_u32 s28, s4, 0x39400e00
	s_addc_u32 s29, s5, 0
	s_add_u32 s30, s4, 0x39400f00
	s_addc_u32 s31, s5, 0
	s_add_u32 s34, s4, 0x39401000
	s_addc_u32 s35, s5, 0
	s_add_u32 s36, s4, 0x39401100
	s_addc_u32 s37, s5, 0
	s_add_u32 s40, s4, 0x39401200
	s_addc_u32 s41, s5, 0
	s_add_u32 s44, s4, 0x39401300
	s_addc_u32 s45, s5, 0
	s_mov_b32 s43, 1
	v_mov_b32_e32 v16, 0
	s_branch .LBB0_80

; #define LAS __attribute__((address_space(3)))
; __device__ __forceinline__ unsigned xb_add(unsigned* p, unsigned v) { return __hip_atomic_fetch_add(p, v, __ATOMIC_RELAXED, __HIP_MEMORY_SCOPE_AGENT); }
; __device__ __forceinline__ unsigned xb_xcc_id() { return (unsigned)__builtin_amdgcn_s_getreg((3 << 11) | 20) & 0xFu; }
; __device__ __forceinline__ void xcd_barrier(unsigned* bar, volatile LAS unsigned* st) {
;     asm volatile("s_waitcnt vmcnt(0)" ::: "memory");
;     __syncthreads();
;     if (threadIdx.x == 0) {
;         const unsigned x = xb_xcc_id();
;         __builtin_amdgcn_s_waitcnt(0);
;         unsigned nloc = st[0], nx = st[1];
;         if (nloc == 0u) { xcd_barrier_complete(bar, x, nloc, nx); st[0] = nloc; st[1] = nx; }
;         const unsigned old = xb_add(&bar[XB_XSUB(x)], 1u);
.LBB0_259:
	s_mul_i32 s0, s82, 10
	s_add_i32 s81, s0, 2
	s_cmp_gt_i32 s88, s81
	s_cselect_b64 s[0:1], -1, 0
	s_cmp_ge_i32 s81, s89
	s_cselect_b64 s[4:5], -1, 0
	s_or_b64 s[0:1], s[0:1], s[4:5]
	s_and_b64 vcc, exec, s[0:1]
	s_cbranch_vccnz .LBB0_314
	v_readlane_b32 s4, v254, 0
	v_readlane_b32 s5, v254, 1
	s_load_dwordx2 s[4:5], s[4:5], 0xb8
	s_waitcnt vmcnt(0)
	s_barrier
	s_mov_b64 s[0:1], exec
	v_readlane_b32 s6, v254, 4
	v_readlane_b32 s7, v254, 5
	s_and_b64 s[6:7], s[0:1], s[6:7]
	s_mov_b64 exec, s[6:7]
	s_cbranch_execz .LBB0_313
	v_readlane_b32 s7, v254, 59
	s_getreg_b32 s6, hwreg(HW_REG_XCC_ID, 0, 4)
	v_mov_b32_e32 v0, s7
	s_waitcnt vmcnt(0) expcnt(0) lgkmcnt(0)
	ds_read_b32 v2, v0
	v_readlane_b32 s7, v254, 60
	s_and_b32 s86, s6, 15
	s_waitcnt lgkmcnt(0)
	v_cmp_ne_u32_e32 vcc, 0, v2
	v_mov_b32_e32 v0, s7
	ds_read_b32 v0, v0
	s_cbranch_vccnz .LBB0_277
	v_readlane_b32 s6, v254, 2
	v_readlane_b32 s7, v254, 3
	s_load_dwordx2 s[10:11], s[6:7], 0x4
	s_add_u32 s6, s4, 0x39400200
	s_addc_u32 s7, s5, 0
	s_add_u32 s8, s4, 0x39400400
	s_addc_u32 s9, s5, 0
	s_waitcnt lgkmcnt(0)
	s_mul_i32 s88, s10, s3
	s_add_u32 s10, s4, 0x39400500
	s_mul_i32 s88, s88, s11
	s_addc_u32 s11, s5, 0
	s_add_u32 s12, s4, 0x39400600
	s_addc_u32 s13, s5, 0
	s_add_u32 s14, s4, 0x39400700
	s_addc_u32 s15, s5, 0
	s_add_u32 s16, s4, 0x39400800
	s_addc_u32 s17, s5, 0
	s_add_u32 s18, s4, 0x39400900
	s_addc_u32 s19, s5, 0
	s_add_u32 s20, s4, 0x39400a00
	s_addc_u32 s21, s5, 0
	s_add_u32 s22, s4, 0x39400b00
	s_addc_u32 s23, s5, 0
	s_add_u32 s24, s4, 0x39400c00
	s_addc_u32 s25, s5, 0
	s_add_u32 s26, s4, 0x39400d00
	s_addc_u32 s27, s5, 0
	s_add_u32 s28, s4, 0x39400e00
	s_addc_u32 s29, s5, 0
	s_add_u32 s30, s4, 0x39400f00
	s_addc_u32 s31, s5, 0
	s_add_u32 s34, s4, 0x39401000
	s_addc_u32 s35, s5, 0
	s_add_u32 s36, s4, 0x39401100
	s_addc_u32 s37, s5, 0
	s_add_u32 s40, s4, 0x39401200
	s_addc_u32 s41, s5, 0
	s_add_u32 s52, s4, 0x39401300
	s_addc_u32 s53, s5, 0
	s_mov_b32 s89, 1
	s_branch .LBB0_265

; #define LAS __attribute__((address_space(3)))
; __device__ __forceinline__ unsigned xb_add(unsigned* p, unsigned v) { return __hip_atomic_fetch_add(p, v, __ATOMIC_RELAXED, __HIP_MEMORY_SCOPE_AGENT); }
; __device__ __forceinline__ unsigned xb_xcc_id() { return (unsigned)__builtin_amdgcn_s_getreg((3 << 11) | 20) & 0xFu; }
; __device__ __forceinline__ void xcd_barrier(unsigned* bar, volatile LAS unsigned* st) {
;     asm volatile("s_waitcnt vmcnt(0)" ::: "memory");
;     __syncthreads();
;     if (threadIdx.x == 0) {
;         const unsigned x = xb_xcc_id();
;         __builtin_amdgcn_s_waitcnt(0);
;         unsigned nloc = st[0], nx = st[1];
;         if (nloc == 0u) { xcd_barrier_complete(bar, x, nloc, nx); st[0] = nloc; st[1] = nx; }
;         const unsigned old = xb_add(&bar[XB_XSUB(x)], 1u);
.LBB0_352:
	v_readlane_b32 s0, v255, 7
	s_add_i32 s81, s0, 3
	s_cmp_lt_i32 s81, s89
	s_cbranch_scc0 .LBB0_406
	v_readlane_b32 s4, v254, 0
	v_readlane_b32 s5, v254, 1
	s_load_dwordx2 s[4:5], s[4:5], 0xb8
	s_waitcnt vmcnt(0)
	s_barrier
	s_mov_b64 s[0:1], exec
	v_readlane_b32 s6, v254, 4
	v_readlane_b32 s7, v254, 5
	s_and_b64 s[6:7], s[0:1], s[6:7]
	s_mov_b64 exec, s[6:7]
	s_cbranch_execz .LBB0_405
	v_readlane_b32 s7, v254, 59
	s_getreg_b32 s6, hwreg(HW_REG_XCC_ID, 0, 4)
	v_mov_b32_e32 v0, s7
	s_waitcnt vmcnt(0) expcnt(0) lgkmcnt(0)
	ds_read_b32 v2, v0
	v_readlane_b32 s7, v254, 60
	s_and_b32 s86, s6, 15
	s_waitcnt lgkmcnt(0)
	v_cmp_ne_u32_e32 vcc, 0, v2
	v_mov_b32_e32 v0, s7
	ds_read_b32 v0, v0
	s_cbranch_vccnz .LBB0_369
	v_readlane_b32 s6, v254, 2
	v_readlane_b32 s7, v254, 3
	s_load_dwordx2 s[10:11], s[6:7], 0x4
	s_add_u32 s6, s4, 0x39400200
	s_addc_u32 s7, s5, 0
	s_add_u32 s8, s4, 0x39400400
	s_addc_u32 s9, s5, 0
	s_waitcnt lgkmcnt(0)
	s_mul_i32 s88, s10, s3
	s_add_u32 s10, s4, 0x39400500
	s_mul_i32 s88, s88, s11
	s_addc_u32 s11, s5, 0
	s_add_u32 s12, s4, 0x39400600
	s_addc_u32 s13, s5, 0
	s_add_u32 s14, s4, 0x39400700
	s_addc_u32 s15, s5, 0
	s_add_u32 s16, s4, 0x39400800
	s_addc_u32 s17, s5, 0
	s_add_u32 s18, s4, 0x39400900
	s_addc_u32 s19, s5, 0
	s_add_u32 s20, s4, 0x39400a00
	s_addc_u32 s21, s5, 0
	s_add_u32 s22, s4, 0x39400b00
	s_addc_u32 s23, s5, 0
	s_add_u32 s24, s4, 0x39400c00
	s_addc_u32 s25, s5, 0
	s_add_u32 s26, s4, 0x39400d00
	s_addc_u32 s27, s5, 0
	s_add_u32 s28, s4, 0x39400e00
	s_addc_u32 s29, s5, 0
	s_add_u32 s30, s4, 0x39400f00
	s_addc_u32 s31, s5, 0
	s_add_u32 s34, s4, 0x39401000
	s_addc_u32 s35, s5, 0
	s_add_u32 s36, s4, 0x39401100
	s_addc_u32 s37, s5, 0
	s_add_u32 s40, s4, 0x39401200
	s_addc_u32 s41, s5, 0
	s_add_u32 s52, s4, 0x39401300
	s_mov_b32 s46, s82
	s_addc_u32 s53, s5, 0
	s_mov_b32 s89, 1
	s_branch .LBB0_357

; #define LAS __attribute__((address_space(3)))
; __device__ __forceinline__ unsigned xb_add(unsigned* p, unsigned v) { return __hip_atomic_fetch_add(p, v, __ATOMIC_RELAXED, __HIP_MEMORY_SCOPE_AGENT); }
; __device__ __forceinline__ unsigned xb_xcc_id() { return (unsigned)__builtin_amdgcn_s_getreg((3 << 11) | 20) & 0xFu; }
; __device__ __forceinline__ void xcd_barrier(unsigned* bar, volatile LAS unsigned* st) {
;     asm volatile("s_waitcnt vmcnt(0)" ::: "memory");
;     __syncthreads();
;     if (threadIdx.x == 0) {
;         const unsigned x = xb_xcc_id();
;         __builtin_amdgcn_s_waitcnt(0);
;         unsigned nloc = st[0], nx = st[1];
;         if (nloc == 0u) { xcd_barrier_complete(bar, x, nloc, nx); st[0] = nloc; st[1] = nx; }
;         const unsigned old = xb_add(&bar[XB_XSUB(x)], 1u);
.LBB0_431:
	v_readlane_b32 s0, v255, 7
	s_add_i32 s81, s0, 4
	s_cmp_ge_i32 s81, s89
	s_cbranch_scc1 .LBB0_485
	v_readlane_b32 s4, v254, 0
	v_readlane_b32 s5, v254, 1
	s_load_dwordx2 s[4:5], s[4:5], 0xb8
	s_waitcnt vmcnt(0)
	s_barrier
	s_mov_b64 s[0:1], exec
	v_readlane_b32 s6, v254, 4
	v_readlane_b32 s7, v254, 5
	s_and_b64 s[6:7], s[0:1], s[6:7]
	s_mov_b64 exec, s[6:7]
	s_cbranch_execz .LBB0_484
	v_readlane_b32 s7, v254, 59
	s_getreg_b32 s6, hwreg(HW_REG_XCC_ID, 0, 4)
	v_mov_b32_e32 v0, s7
	s_waitcnt vmcnt(0) expcnt(0) lgkmcnt(0)
	ds_read_b32 v2, v0
	v_readlane_b32 s7, v254, 60
	s_and_b32 s86, s6, 15
	s_waitcnt lgkmcnt(0)
	v_cmp_ne_u32_e32 vcc, 0, v2
	v_mov_b32_e32 v0, s7
	ds_read_b32 v0, v0
	s_cbranch_vccnz .LBB0_448
	v_readlane_b32 s6, v254, 2
	v_readlane_b32 s7, v254, 3
	s_load_dwordx2 s[10:11], s[6:7], 0x4
	s_add_u32 s6, s4, 0x39400200
	s_addc_u32 s7, s5, 0
	s_add_u32 s8, s4, 0x39400400
	s_addc_u32 s9, s5, 0
	s_waitcnt lgkmcnt(0)
	s_mul_i32 s88, s10, s3
	s_add_u32 s10, s4, 0x39400500
	s_mul_i32 s88, s88, s11
	s_addc_u32 s11, s5, 0
	s_add_u32 s12, s4, 0x39400600
	s_addc_u32 s13, s5, 0
	s_add_u32 s14, s4, 0x39400700
	s_addc_u32 s15, s5, 0
	s_add_u32 s16, s4, 0x39400800
	s_addc_u32 s17, s5, 0
	s_add_u32 s18, s4, 0x39400900
	s_addc_u32 s19, s5, 0
	s_add_u32 s20, s4, 0x39400a00
	s_addc_u32 s21, s5, 0
	s_add_u32 s22, s4, 0x39400b00
	s_addc_u32 s23, s5, 0
	s_add_u32 s24, s4, 0x39400c00
	s_addc_u32 s25, s5, 0
	s_add_u32 s26, s4, 0x39400d00
	s_addc_u32 s27, s5, 0
	s_add_u32 s28, s4, 0x39400e00
	s_addc_u32 s29, s5, 0
	s_add_u32 s30, s4, 0x39400f00
	s_addc_u32 s31, s5, 0
	s_add_u32 s34, s4, 0x39401000
	s_addc_u32 s35, s5, 0
	s_add_u32 s36, s4, 0x39401100
	s_addc_u32 s37, s5, 0
	s_add_u32 s40, s4, 0x39401200
	s_addc_u32 s41, s5, 0
	s_add_u32 s52, s4, 0x39401300
	s_addc_u32 s53, s5, 0
	s_mov_b32 s89, 1
	s_branch .LBB0_436

; #define LAS __attribute__((address_space(3)))
; __device__ __forceinline__ unsigned xb_add(unsigned* p, unsigned v) { return __hip_atomic_fetch_add(p, v, __ATOMIC_RELAXED, __HIP_MEMORY_SCOPE_AGENT); }
; __device__ __forceinline__ unsigned xb_xcc_id() { return (unsigned)__builtin_amdgcn_s_getreg((3 << 11) | 20) & 0xFu; }
; __device__ __forceinline__ void xcd_barrier(unsigned* bar, volatile LAS unsigned* st) {
;     asm volatile("s_waitcnt vmcnt(0)" ::: "memory");
;     __syncthreads();
;     if (threadIdx.x == 0) {
;         const unsigned x = xb_xcc_id();
;         __builtin_amdgcn_s_waitcnt(0);
;         unsigned nloc = st[0], nx = st[1];
;         if (nloc == 0u) { xcd_barrier_complete(bar, x, nloc, nx); st[0] = nloc; st[1] = nx; }
;         const unsigned old = xb_add(&bar[XB_XSUB(x)], 1u);
.LBB0_508:
	v_readlane_b32 s0, v255, 7
	s_add_i32 s81, s0, 5
	s_cmp_ge_i32 s81, s89
	s_cbranch_scc1 .LBB0_562
	v_readlane_b32 s4, v254, 0
	v_readlane_b32 s5, v254, 1
	s_load_dwordx2 s[4:5], s[4:5], 0xb8
	s_waitcnt vmcnt(0)
	s_waitcnt vmcnt(0)
	s_barrier
	s_mov_b64 s[0:1], exec
	v_readlane_b32 s6, v254, 4
	v_readlane_b32 s7, v254, 5
	s_and_b64 s[6:7], s[0:1], s[6:7]
	s_mov_b64 exec, s[6:7]
	s_cbranch_execz .LBB0_561
	v_readlane_b32 s7, v254, 59
	s_getreg_b32 s6, hwreg(HW_REG_XCC_ID, 0, 4)
	v_mov_b32_e32 v0, s7
	s_waitcnt vmcnt(0) expcnt(0) lgkmcnt(0)
	ds_read_b32 v2, v0
	v_readlane_b32 s7, v254, 60
	s_and_b32 s86, s6, 15
	s_waitcnt lgkmcnt(0)
	v_cmp_ne_u32_e32 vcc, 0, v2
	v_mov_b32_e32 v0, s7
	ds_read_b32 v0, v0
	s_cbranch_vccnz .LBB0_525
	v_readlane_b32 s6, v254, 2
	v_readlane_b32 s7, v254, 3
	s_load_dwordx2 s[10:11], s[6:7], 0x4
	s_add_u32 s6, s4, 0x39400200
	s_addc_u32 s7, s5, 0
	s_add_u32 s8, s4, 0x39400400
	s_addc_u32 s9, s5, 0
	s_waitcnt lgkmcnt(0)
	s_mul_i32 s88, s10, s3
	s_add_u32 s10, s4, 0x39400500
	s_mul_i32 s88, s88, s11
	s_addc_u32 s11, s5, 0
	s_add_u32 s12, s4, 0x39400600
	s_addc_u32 s13, s5, 0
	s_add_u32 s14, s4, 0x39400700
	s_addc_u32 s15, s5, 0
	s_add_u32 s16, s4, 0x39400800
	s_addc_u32 s17, s5, 0
	s_add_u32 s18, s4, 0x39400900
	s_addc_u32 s19, s5, 0
	s_add_u32 s20, s4, 0x39400a00
	s_addc_u32 s21, s5, 0
	s_add_u32 s22, s4, 0x39400b00
	s_addc_u32 s23, s5, 0
	s_add_u32 s24, s4, 0x39400c00
	s_addc_u32 s25, s5, 0
	s_add_u32 s26, s4, 0x39400d00
	s_addc_u32 s27, s5, 0
	s_add_u32 s28, s4, 0x39400e00
	s_addc_u32 s29, s5, 0
	s_add_u32 s30, s4, 0x39400f00
	s_addc_u32 s31, s5, 0
	s_add_u32 s34, s4, 0x39401000
	s_addc_u32 s35, s5, 0
	s_add_u32 s36, s4, 0x39401100
	s_addc_u32 s37, s5, 0
	s_add_u32 s40, s4, 0x39401200
	s_addc_u32 s41, s5, 0
	s_add_u32 s52, s4, 0x39401300
	s_addc_u32 s53, s5, 0
	s_mov_b32 s89, 1
	s_branch .LBB0_513

; #define LAS __attribute__((address_space(3)))
; __device__ __forceinline__ unsigned xb_add(unsigned* p, unsigned v) { return __hip_atomic_fetch_add(p, v, __ATOMIC_RELAXED, __HIP_MEMORY_SCOPE_AGENT); }
; __device__ __forceinline__ unsigned xb_xcc_id() { return (unsigned)__builtin_amdgcn_s_getreg((3 << 11) | 20) & 0xFu; }
; __device__ __forceinline__ void xcd_barrier(unsigned* bar, volatile LAS unsigned* st) {
;     asm volatile("s_waitcnt vmcnt(0)" ::: "memory");
;     __syncthreads();
;     if (threadIdx.x == 0) {
;         const unsigned x = xb_xcc_id();
;         __builtin_amdgcn_s_waitcnt(0);
;         unsigned nloc = st[0], nx = st[1];
;         if (nloc == 0u) { xcd_barrier_complete(bar, x, nloc, nx); st[0] = nloc; st[1] = nx; }
;         const unsigned old = xb_add(&bar[XB_XSUB(x)], 1u);
; __global__ void __launch_bounds__(512, 2) fwd_megakernel(Args AV) {
;     ...
;             __syncthreads();
.LBB0_588:
	v_readlane_b32 s0, v255, 7
	s_add_i32 s81, s0, 6
	s_cmp_lt_i32 s81, s89
	s_barrier
	s_cbranch_scc0 .LBB0_642
	v_readlane_b32 s4, v254, 0
	v_readlane_b32 s5, v254, 1
	s_load_dwordx2 s[4:5], s[4:5], 0xb8
	s_waitcnt vmcnt(0)
	s_barrier
	s_mov_b64 s[0:1], exec
	v_readlane_b32 s6, v254, 4
	v_readlane_b32 s7, v254, 5
	s_and_b64 s[6:7], s[0:1], s[6:7]
	s_mov_b64 exec, s[6:7]
	s_cbranch_execz .LBB0_641
	v_readlane_b32 s7, v254, 59
	s_getreg_b32 s6, hwreg(HW_REG_XCC_ID, 0, 4)
	v_mov_b32_e32 v0, s7
	s_waitcnt vmcnt(0) expcnt(0) lgkmcnt(0)
	ds_read_b32 v2, v0
	v_readlane_b32 s7, v254, 60
	s_and_b32 s86, s6, 15
	s_waitcnt lgkmcnt(0)
	v_cmp_ne_u32_e32 vcc, 0, v2
	v_mov_b32_e32 v0, s7
	ds_read_b32 v0, v0
	s_cbranch_vccnz .LBB0_605
	v_readlane_b32 s6, v254, 2
	v_readlane_b32 s7, v254, 3
	s_load_dwordx2 s[10:11], s[6:7], 0x4
	s_add_u32 s6, s4, 0x39400200
	s_addc_u32 s7, s5, 0
	s_add_u32 s8, s4, 0x39400400
	s_addc_u32 s9, s5, 0
	s_waitcnt lgkmcnt(0)
	s_mul_i32 s88, s10, s3
	s_add_u32 s10, s4, 0x39400500
	s_mul_i32 s88, s88, s11
	s_addc_u32 s11, s5, 0
	s_add_u32 s12, s4, 0x39400600
	s_addc_u32 s13, s5, 0
	s_add_u32 s14, s4, 0x39400700
	s_addc_u32 s15, s5, 0
	s_add_u32 s16, s4, 0x39400800
	s_addc_u32 s17, s5, 0
	s_add_u32 s18, s4, 0x39400900
	s_addc_u32 s19, s5, 0
	s_add_u32 s20, s4, 0x39400a00
	s_addc_u32 s21, s5, 0
	s_add_u32 s22, s4, 0x39400b00
	s_addc_u32 s23, s5, 0
	s_add_u32 s24, s4, 0x39400c00
	s_addc_u32 s25, s5, 0
	s_add_u32 s26, s4, 0x39400d00
	s_addc_u32 s27, s5, 0
	s_add_u32 s28, s4, 0x39400e00
	s_addc_u32 s29, s5, 0
	s_add_u32 s30, s4, 0x39400f00
	s_addc_u32 s31, s5, 0
	s_add_u32 s34, s4, 0x39401000
	s_addc_u32 s35, s5, 0
	s_add_u32 s36, s4, 0x39401100
	s_addc_u32 s37, s5, 0
	s_add_u32 s40, s4, 0x39401200
	s_addc_u32 s41, s5, 0
	s_add_u32 s52, s4, 0x39401300
	s_mov_b32 s46, s82
	s_addc_u32 s53, s5, 0
	s_mov_b32 s89, 1
	s_branch .LBB0_593

; #define LAS __attribute__((address_space(3)))
; __device__ __forceinline__ unsigned xb_add(unsigned* p, unsigned v) { return __hip_atomic_fetch_add(p, v, __ATOMIC_RELAXED, __HIP_MEMORY_SCOPE_AGENT); }
; __device__ __forceinline__ unsigned xb_xcc_id() { return (unsigned)__builtin_amdgcn_s_getreg((3 << 11) | 20) & 0xFu; }
; __device__ __forceinline__ void xcd_barrier(unsigned* bar, volatile LAS unsigned* st) {
;     asm volatile("s_waitcnt vmcnt(0)" ::: "memory");
;     __syncthreads();
;     if (threadIdx.x == 0) {
;         const unsigned x = xb_xcc_id();
;         __builtin_amdgcn_s_waitcnt(0);
;         unsigned nloc = st[0], nx = st[1];
;         if (nloc == 0u) { xcd_barrier_complete(bar, x, nloc, nx); st[0] = nloc; st[1] = nx; }
;         const unsigned old = xb_add(&bar[XB_XSUB(x)], 1u);
.LBB0_696:
	v_readlane_b32 s0, v255, 7
	s_add_i32 s0, s0, 7
	s_cmp_lt_i32 s0, s89
	s_cbranch_scc0 .LBB0_750
	v_readlane_b32 s4, v254, 0
	v_readlane_b32 s5, v254, 1
	s_load_dwordx2 s[4:5], s[4:5], 0xb8
	s_waitcnt vmcnt(0)
	s_waitcnt vmcnt(0)
	s_barrier
	s_mov_b64 s[0:1], exec
	v_readlane_b32 s6, v254, 4
	v_readlane_b32 s7, v254, 5
	s_and_b64 s[6:7], s[0:1], s[6:7]
	s_mov_b64 exec, s[6:7]
	s_cbranch_execz .LBB0_749
	v_readlane_b32 s7, v254, 59
	s_getreg_b32 s6, hwreg(HW_REG_XCC_ID, 0, 4)
	v_mov_b32_e32 v0, s7
	s_waitcnt vmcnt(0) expcnt(0) lgkmcnt(0)
	ds_read_b32 v2, v0
	v_readlane_b32 s7, v254, 60
	s_and_b32 s81, s6, 15
	s_waitcnt lgkmcnt(0)
	v_cmp_ne_u32_e32 vcc, 0, v2
	v_mov_b32_e32 v0, s7
	ds_read_b32 v0, v0
	s_cbranch_vccnz .LBB0_713
	v_readlane_b32 s6, v254, 2
	v_readlane_b32 s7, v254, 3
	s_load_dwordx2 s[10:11], s[6:7], 0x4
	s_add_u32 s6, s4, 0x39400200
	s_addc_u32 s7, s5, 0
	s_add_u32 s8, s4, 0x39400400
	s_addc_u32 s9, s5, 0
	s_waitcnt lgkmcnt(0)
	s_mul_i32 s86, s10, s3
	s_add_u32 s10, s4, 0x39400500
	s_mul_i32 s86, s86, s11
	s_addc_u32 s11, s5, 0
	s_add_u32 s12, s4, 0x39400600
	s_addc_u32 s13, s5, 0
	s_add_u32 s14, s4, 0x39400700
	s_addc_u32 s15, s5, 0
	s_add_u32 s16, s4, 0x39400800
	s_addc_u32 s17, s5, 0
	s_add_u32 s18, s4, 0x39400900
	s_addc_u32 s19, s5, 0
	s_add_u32 s20, s4, 0x39400a00
	s_addc_u32 s21, s5, 0
	s_add_u32 s22, s4, 0x39400b00
	s_addc_u32 s23, s5, 0
	s_add_u32 s24, s4, 0x39400c00
	s_addc_u32 s25, s5, 0
	s_add_u32 s26, s4, 0x39400d00
	s_addc_u32 s27, s5, 0
	s_add_u32 s28, s4, 0x39400e00
	s_addc_u32 s29, s5, 0
	s_add_u32 s30, s4, 0x39400f00
	s_addc_u32 s31, s5, 0
	s_add_u32 s34, s4, 0x39401000
	s_addc_u32 s35, s5, 0
	s_add_u32 s36, s4, 0x39401100
	s_addc_u32 s37, s5, 0
	s_add_u32 s40, s4, 0x39401200
	s_addc_u32 s41, s5, 0
	s_add_u32 s52, s4, 0x39401300
	s_mov_b32 s46, s82
	s_addc_u32 s53, s5, 0
	s_mov_b32 s88, 1
	s_branch .LBB0_701

; #define LAS __attribute__((address_space(3)))
; __device__ __forceinline__ unsigned xb_add(unsigned* p, unsigned v) { return __hip_atomic_fetch_add(p, v, __ATOMIC_RELAXED, __HIP_MEMORY_SCOPE_AGENT); }
; __device__ __forceinline__ unsigned xb_xcc_id() { return (unsigned)__builtin_amdgcn_s_getreg((3 << 11) | 20) & 0xFu; }
; __device__ __forceinline__ void xcd_barrier(unsigned* bar, volatile LAS unsigned* st) {
;     asm volatile("s_waitcnt vmcnt(0)" ::: "memory");
;     __syncthreads();
;     if (threadIdx.x == 0) {
;         const unsigned x = xb_xcc_id();
;         __builtin_amdgcn_s_waitcnt(0);
;         unsigned nloc = st[0], nx = st[1];
;         if (nloc == 0u) { xcd_barrier_complete(bar, x, nloc, nx); st[0] = nloc; st[1] = nx; }
;         const unsigned old = xb_add(&bar[XB_XSUB(x)], 1u);
.LBB0_782:
	v_readlane_b32 s0, v255, 7
	s_add_i32 s81, s0, 9
	s_cmp_ge_i32 s81, s89
	s_cbranch_scc1 .LBB0_836
	v_readlane_b32 s4, v254, 0
	v_readlane_b32 s5, v254, 1
	s_load_dwordx2 s[4:5], s[4:5], 0xb8
	s_waitcnt vmcnt(0)
	s_waitcnt vmcnt(0)
	s_barrier
	s_mov_b64 s[0:1], exec
	v_readlane_b32 s6, v254, 4
	v_readlane_b32 s7, v254, 5
	s_and_b64 s[6:7], s[0:1], s[6:7]
	s_mov_b64 exec, s[6:7]
	s_cbranch_execz .LBB0_835
	v_readlane_b32 s7, v254, 59
	s_getreg_b32 s6, hwreg(HW_REG_XCC_ID, 0, 4)
	v_mov_b32_e32 v0, s7
	s_waitcnt vmcnt(0) expcnt(0) lgkmcnt(0)
	ds_read_b32 v2, v0
	v_readlane_b32 s7, v254, 60
	s_and_b32 s86, s6, 15
	s_waitcnt lgkmcnt(0)
	v_cmp_ne_u32_e32 vcc, 0, v2
	v_mov_b32_e32 v0, s7
	ds_read_b32 v0, v0
	s_cbranch_vccnz .LBB0_799
	v_readlane_b32 s6, v254, 2
	v_readlane_b32 s7, v254, 3
	s_load_dwordx2 s[10:11], s[6:7], 0x4
	s_add_u32 s6, s4, 0x39400200
	s_addc_u32 s7, s5, 0
	s_add_u32 s8, s4, 0x39400400
	s_addc_u32 s9, s5, 0
	s_waitcnt lgkmcnt(0)
	s_mul_i32 s88, s10, s3
	s_add_u32 s10, s4, 0x39400500
	s_mul_i32 s88, s88, s11
	s_addc_u32 s11, s5, 0
	s_add_u32 s12, s4, 0x39400600
	s_addc_u32 s13, s5, 0
	s_add_u32 s14, s4, 0x39400700
	s_addc_u32 s15, s5, 0
	s_add_u32 s16, s4, 0x39400800
	s_addc_u32 s17, s5, 0
	s_add_u32 s18, s4, 0x39400900
	s_addc_u32 s19, s5, 0
	s_add_u32 s20, s4, 0x39400a00
	s_addc_u32 s21, s5, 0
	s_add_u32 s22, s4, 0x39400b00
	s_addc_u32 s23, s5, 0
	s_add_u32 s24, s4, 0x39400c00
	s_addc_u32 s25, s5, 0
	s_add_u32 s26, s4, 0x39400d00
	s_addc_u32 s27, s5, 0
	s_add_u32 s28, s4, 0x39400e00
	s_addc_u32 s29, s5, 0
	s_add_u32 s30, s4, 0x39400f00
	s_addc_u32 s31, s5, 0
	s_add_u32 s34, s4, 0x39401000
	s_addc_u32 s35, s5, 0
	s_add_u32 s36, s4, 0x39401100
	s_addc_u32 s37, s5, 0
	s_add_u32 s40, s4, 0x39401200
	s_addc_u32 s41, s5, 0
	s_add_u32 s52, s4, 0x39401300
	s_mov_b32 s46, s82
	s_addc_u32 s53, s5, 0
	s_mov_b32 s89, 1
	s_branch .LBB0_787

; #define LAS __attribute__((address_space(3)))
; __device__ __forceinline__ unsigned xb_add(unsigned* p, unsigned v) { return __hip_atomic_fetch_add(p, v, __ATOMIC_RELAXED, __HIP_MEMORY_SCOPE_AGENT); }
; __device__ __forceinline__ unsigned xb_xcc_id() { return (unsigned)__builtin_amdgcn_s_getreg((3 << 11) | 20) & 0xFu; }
; __device__ __forceinline__ void xcd_barrier(unsigned* bar, volatile LAS unsigned* st) {
;     asm volatile("s_waitcnt vmcnt(0)" ::: "memory");
;     __syncthreads();
;     if (threadIdx.x == 0) {
;         const unsigned x = xb_xcc_id();
;         __builtin_amdgcn_s_waitcnt(0);
;         unsigned nloc = st[0], nx = st[1];
;         if (nloc == 0u) { xcd_barrier_complete(bar, x, nloc, nx); st[0] = nloc; st[1] = nx; }
;         const unsigned old = xb_add(&bar[XB_XSUB(x)], 1u);
.LBB0_855:
	v_readlane_b32 s0, v255, 7
	s_add_i32 s81, s0, 10
	s_cmp_ge_i32 s81, s89
	s_cbranch_scc1 .LBB0_909
	v_readlane_b32 s4, v254, 0
	v_readlane_b32 s5, v254, 1
	s_load_dwordx2 s[4:5], s[4:5], 0xb8
	s_waitcnt vmcnt(0)
	s_waitcnt vmcnt(0)
	s_barrier
	s_mov_b64 s[0:1], exec
	v_readlane_b32 s6, v254, 4
	v_readlane_b32 s7, v254, 5
	s_and_b64 s[6:7], s[0:1], s[6:7]
	s_mov_b64 exec, s[6:7]
	s_cbranch_execz .LBB0_908
	v_readlane_b32 s7, v254, 59
	s_getreg_b32 s6, hwreg(HW_REG_XCC_ID, 0, 4)
	v_mov_b32_e32 v0, s7
	s_waitcnt vmcnt(0) expcnt(0) lgkmcnt(0)
	ds_read_b32 v2, v0
	v_readlane_b32 s7, v254, 60
	s_and_b32 s86, s6, 15
	s_waitcnt lgkmcnt(0)
	v_cmp_ne_u32_e32 vcc, 0, v2
	v_mov_b32_e32 v0, s7
	ds_read_b32 v0, v0
	s_cbranch_vccnz .LBB0_872
	v_readlane_b32 s6, v254, 2
	v_readlane_b32 s7, v254, 3
	s_load_dwordx2 s[10:11], s[6:7], 0x4
	s_add_u32 s6, s4, 0x39400200
	s_addc_u32 s7, s5, 0
	s_add_u32 s8, s4, 0x39400400
	s_addc_u32 s9, s5, 0
	s_waitcnt lgkmcnt(0)
	s_mul_i32 s88, s10, s3
	s_add_u32 s10, s4, 0x39400500
	s_mul_i32 s88, s88, s11
	s_addc_u32 s11, s5, 0
	s_add_u32 s12, s4, 0x39400600
	s_addc_u32 s13, s5, 0
	s_add_u32 s14, s4, 0x39400700
	s_addc_u32 s15, s5, 0
	s_add_u32 s16, s4, 0x39400800
	s_addc_u32 s17, s5, 0
	s_add_u32 s18, s4, 0x39400900
	s_addc_u32 s19, s5, 0
	s_add_u32 s20, s4, 0x39400a00
	s_addc_u32 s21, s5, 0
	s_add_u32 s22, s4, 0x39400b00
	s_addc_u32 s23, s5, 0
	s_add_u32 s24, s4, 0x39400c00
	s_addc_u32 s25, s5, 0
	s_add_u32 s26, s4, 0x39400d00
	s_addc_u32 s27, s5, 0
	s_add_u32 s28, s4, 0x39400e00
	s_addc_u32 s29, s5, 0
	s_add_u32 s30, s4, 0x39400f00
	s_addc_u32 s31, s5, 0
	s_add_u32 s34, s4, 0x39401000
	s_addc_u32 s35, s5, 0
	s_add_u32 s36, s4, 0x39401100
	s_addc_u32 s37, s5, 0
	s_add_u32 s40, s4, 0x39401200
	s_addc_u32 s41, s5, 0
	s_add_u32 s52, s4, 0x39401300
	s_mov_b32 s46, s82
	s_addc_u32 s53, s5, 0
	s_mov_b32 s89, 1
	s_branch .LBB0_860
